# GEMM main loops: per-segment s_setprio flips deleted, one static s_setprio 1 for waves 0-3 before each loop (reset after it)
# speedup vs baseline: 1.0125x; 1.0012x over previous
; template <class Epi>
; __device__ __forceinline__ void gemm_phase(LAS unsigned char* lds, const Gemm g, const StaticOrder& S, const Epi& E) {
;     ...
; #pragma unroll
;         for (int a = 0; a < 2; ++a)
; #pragma unroll
;             for (int b = 0; b < 2; ++b)
; #pragma unroll
;                 for (int m = 0; m < 4; ++m)
; #pragma unroll
;                     for (int n = 0; n < 2; ++n) acc[a][b][m][n] = (f32x4){0.f, 0.f, 0.f, 0.f};
;         cur = nxt; cA = nA; cB = nB; ++ui;
.LBB0_117:
	v_mov_b32_e32 v127, 0
	s_andn2_b64 vcc, exec, s[6:7]
	v_mov_b32_e32 v126, v127
	v_mov_b32_e32 v125, v127
	v_mov_b32_e32 v124, v127
	v_mov_b32_e32 v123, v127
	v_mov_b32_e32 v122, v127
	v_mov_b32_e32 v121, v127
	v_mov_b32_e32 v120, v127
	v_mov_b32_e32 v111, v127
	v_mov_b32_e32 v110, v127
	v_mov_b32_e32 v109, v127
	v_mov_b32_e32 v108, v127
	v_mov_b32_e32 v107, v127
	v_mov_b32_e32 v106, v127
	v_mov_b32_e32 v105, v127
	v_mov_b32_e32 v104, v127
	v_mov_b32_e32 v95, v127
	v_mov_b32_e32 v94, v127
	v_mov_b32_e32 v93, v127
	v_mov_b32_e32 v92, v127
	v_mov_b32_e32 v91, v127
	v_mov_b32_e32 v90, v127
	v_mov_b32_e32 v89, v127
	v_mov_b32_e32 v88, v127
	v_mov_b32_e32 v79, v127
	v_mov_b32_e32 v78, v127
	v_mov_b32_e32 v77, v127
	v_mov_b32_e32 v76, v127
	v_mov_b32_e32 v75, v127
	v_mov_b32_e32 v74, v127
	v_mov_b32_e32 v73, v127
	v_mov_b32_e32 v72, v127
	v_mov_b32_e32 v119, v127
	v_mov_b32_e32 v118, v127
	v_mov_b32_e32 v117, v127
	v_mov_b32_e32 v116, v127
	v_mov_b32_e32 v115, v127
	v_mov_b32_e32 v114, v127
	v_mov_b32_e32 v113, v127
	v_mov_b32_e32 v112, v127
	v_mov_b32_e32 v103, v127
	v_mov_b32_e32 v102, v127
	v_mov_b32_e32 v101, v127
	v_mov_b32_e32 v100, v127
	v_mov_b32_e32 v99, v127
	v_mov_b32_e32 v98, v127
	v_mov_b32_e32 v97, v127
	v_mov_b32_e32 v96, v127
	v_mov_b32_e32 v87, v127
	v_mov_b32_e32 v86, v127
	v_mov_b32_e32 v85, v127
	v_mov_b32_e32 v84, v127
	v_mov_b32_e32 v83, v127
	v_mov_b32_e32 v82, v127
	v_mov_b32_e32 v81, v127
	v_mov_b32_e32 v80, v127
	v_mov_b32_e32 v71, v127
	v_mov_b32_e32 v70, v127
	v_mov_b32_e32 v69, v127
	v_mov_b32_e32 v68, v127
	v_mov_b32_e32 v67, v127
	v_mov_b32_e32 v66, v127
	v_mov_b32_e32 v65, v127
	v_mov_b32_e32 v64, v127
	v_mov_b32_e32 v63, v127
	v_mov_b32_e32 v62, v127
	v_mov_b32_e32 v61, v127
	v_mov_b32_e32 v60, v127
	v_mov_b32_e32 v59, v127
	v_mov_b32_e32 v58, v127
	v_mov_b32_e32 v57, v127
	v_mov_b32_e32 v56, v127
	v_mov_b32_e32 v47, v127
	v_mov_b32_e32 v46, v127
	v_mov_b32_e32 v45, v127
	v_mov_b32_e32 v44, v127
	v_mov_b32_e32 v43, v127
	v_mov_b32_e32 v42, v127
	v_mov_b32_e32 v41, v127
	v_mov_b32_e32 v40, v127
	v_mov_b32_e32 v31, v127
	v_mov_b32_e32 v30, v127
	v_mov_b32_e32 v29, v127
	v_mov_b32_e32 v28, v127
	v_mov_b32_e32 v27, v127
	v_mov_b32_e32 v26, v127
	v_mov_b32_e32 v25, v127
	v_mov_b32_e32 v24, v127
	v_mov_b32_e32 v15, v127
	v_mov_b32_e32 v14, v127
	v_mov_b32_e32 v13, v127
	v_mov_b32_e32 v12, v127
	v_mov_b32_e32 v11, v127
	v_mov_b32_e32 v10, v127
	v_mov_b32_e32 v9, v127
	v_mov_b32_e32 v8, v127
	v_mov_b32_e32 v55, v127
	v_mov_b32_e32 v54, v127
	v_mov_b32_e32 v53, v127
	v_mov_b32_e32 v52, v127
	v_mov_b32_e32 v51, v127
	v_mov_b32_e32 v50, v127
	v_mov_b32_e32 v49, v127
	v_mov_b32_e32 v48, v127
	v_mov_b32_e32 v39, v127
	v_mov_b32_e32 v38, v127
	v_mov_b32_e32 v37, v127
	v_mov_b32_e32 v36, v127
	v_mov_b32_e32 v35, v127
	v_mov_b32_e32 v34, v127
	v_mov_b32_e32 v33, v127
	v_mov_b32_e32 v32, v127
	v_mov_b32_e32 v23, v127
	v_mov_b32_e32 v22, v127
	v_mov_b32_e32 v21, v127
	v_mov_b32_e32 v20, v127
	v_mov_b32_e32 v19, v127
	v_mov_b32_e32 v18, v127
	v_mov_b32_e32 v17, v127
	v_mov_b32_e32 v16, v127
	v_mov_b32_e32 v7, v127
	v_mov_b32_e32 v6, v127
	v_mov_b32_e32 v5, v127
	v_mov_b32_e32 v4, v127
	v_mov_b32_e32 v3, v127
	v_mov_b32_e32 v2, v127
	s_waitcnt lgkmcnt(0)
	v_mov_b32_e32 v1, v127
	v_mov_b32_e32 v0, v127
	s_cbranch_vccnz .LBB0_120
	s_add_u32 s39, s14, 0x100
	s_addc_u32 s40, s15, 0
	s_add_u32 s14, s16, 0x80
	v_mov_b32_e32 v0, 0
	s_addc_u32 s15, s17, 0
	s_mov_b32 s16, 0
	v_mov_b32_e32 v1, v0
	v_mov_b32_e32 v2, v0
	v_mov_b32_e32 v3, v0
	v_mov_b32_e32 v4, v0
	v_mov_b32_e32 v5, v0
	v_mov_b32_e32 v6, v0
	v_mov_b32_e32 v7, v0
	v_mov_b32_e32 v16, v0
	v_mov_b32_e32 v17, v0
	v_mov_b32_e32 v18, v0
	v_mov_b32_e32 v19, v0
	v_mov_b32_e32 v20, v0
	v_mov_b32_e32 v21, v0
	v_mov_b32_e32 v22, v0
	v_mov_b32_e32 v23, v0
	v_mov_b32_e32 v32, v0
	v_mov_b32_e32 v33, v0
	v_mov_b32_e32 v34, v0
	v_mov_b32_e32 v35, v0
	v_mov_b32_e32 v36, v0
	v_mov_b32_e32 v37, v0
	v_mov_b32_e32 v38, v0
	v_mov_b32_e32 v39, v0
	v_mov_b32_e32 v48, v0
	v_mov_b32_e32 v49, v0
	v_mov_b32_e32 v50, v0
	v_mov_b32_e32 v51, v0
	v_mov_b32_e32 v52, v0
	v_mov_b32_e32 v53, v0
	v_mov_b32_e32 v54, v0
	v_mov_b32_e32 v55, v0
	v_mov_b32_e32 v8, v0
	v_mov_b32_e32 v9, v0
	v_mov_b32_e32 v10, v0
	v_mov_b32_e32 v11, v0
	v_mov_b32_e32 v12, v0
	v_mov_b32_e32 v13, v0
	v_mov_b32_e32 v14, v0
	v_mov_b32_e32 v15, v0
	v_mov_b32_e32 v24, v0
	v_mov_b32_e32 v25, v0
	v_mov_b32_e32 v26, v0
	v_mov_b32_e32 v27, v0
	v_mov_b32_e32 v28, v0
	v_mov_b32_e32 v29, v0
	v_mov_b32_e32 v30, v0
	v_mov_b32_e32 v31, v0
	v_mov_b32_e32 v40, v0
	v_mov_b32_e32 v41, v0
	v_mov_b32_e32 v42, v0
	v_mov_b32_e32 v43, v0
	v_mov_b32_e32 v44, v0
	v_mov_b32_e32 v45, v0
	v_mov_b32_e32 v46, v0
	v_mov_b32_e32 v47, v0
	v_mov_b32_e32 v56, v0
	v_mov_b32_e32 v57, v0
	v_mov_b32_e32 v58, v0
	v_mov_b32_e32 v59, v0
	v_mov_b32_e32 v60, v0
	v_mov_b32_e32 v61, v0
	v_mov_b32_e32 v62, v0
	v_mov_b32_e32 v63, v0
	v_mov_b32_e32 v64, v0
	v_mov_b32_e32 v65, v0
	v_mov_b32_e32 v66, v0
	v_mov_b32_e32 v67, v0
	v_mov_b32_e32 v68, v0
	v_mov_b32_e32 v69, v0
	v_mov_b32_e32 v70, v0
	v_mov_b32_e32 v71, v0
	v_mov_b32_e32 v80, v0
	v_mov_b32_e32 v81, v0
	v_mov_b32_e32 v82, v0
	v_mov_b32_e32 v83, v0
	v_mov_b32_e32 v84, v0
	v_mov_b32_e32 v85, v0
	v_mov_b32_e32 v86, v0
	v_mov_b32_e32 v87, v0
	v_mov_b32_e32 v96, v0
	v_mov_b32_e32 v97, v0
	v_mov_b32_e32 v98, v0
	v_mov_b32_e32 v99, v0
	v_mov_b32_e32 v100, v0
	v_mov_b32_e32 v101, v0
	v_mov_b32_e32 v102, v0
	v_mov_b32_e32 v103, v0
	v_mov_b32_e32 v112, v0
	v_mov_b32_e32 v113, v0
	v_mov_b32_e32 v114, v0
	v_mov_b32_e32 v115, v0
	v_mov_b32_e32 v116, v0
	v_mov_b32_e32 v117, v0
	v_mov_b32_e32 v118, v0
	v_mov_b32_e32 v119, v0
	v_mov_b32_e32 v72, v0
	v_mov_b32_e32 v73, v0
	v_mov_b32_e32 v74, v0
	v_mov_b32_e32 v75, v0
	v_mov_b32_e32 v76, v0
	v_mov_b32_e32 v77, v0
	v_mov_b32_e32 v78, v0
	v_mov_b32_e32 v79, v0
	v_mov_b32_e32 v88, v0
	v_mov_b32_e32 v89, v0
	v_mov_b32_e32 v90, v0
	v_mov_b32_e32 v91, v0
	v_mov_b32_e32 v92, v0
	v_mov_b32_e32 v93, v0
	v_mov_b32_e32 v94, v0
	v_mov_b32_e32 v95, v0
	v_mov_b32_e32 v104, v0
	v_mov_b32_e32 v105, v0
	v_mov_b32_e32 v106, v0
	v_mov_b32_e32 v107, v0
	v_mov_b32_e32 v108, v0
	v_mov_b32_e32 v109, v0
	v_mov_b32_e32 v110, v0
	v_mov_b32_e32 v111, v0
	v_mov_b32_e32 v120, v0
	v_mov_b32_e32 v121, v0
	v_mov_b32_e32 v122, v0
	v_mov_b32_e32 v123, v0
	v_mov_b32_e32 v124, v0
	v_mov_b32_e32 v125, v0
	v_mov_b32_e32 v126, v0
	v_mov_b32_e32 v127, v0
	s_mov_b64 s[44:45], 0x80
	v_readfirstlane_b32 s90, v192
	s_lshr_b32 s90, s90, 8
	s_cmp_eq_u32 s90, 0
	s_cbranch_scc0 .Lprio_skip_0
	s_setprio 1

; template <class Epi>
; __device__ __forceinline__ void gemm_phase(LAS unsigned char* lds, const Gemm g, const StaticOrder& S, const Epi& E) {
;     ...
;         const bool has_next = S.next(ui + 1, nxt);
;         const char* nA = has_next ? (const char*)g.A + (size_t)nxt.pm * tstep : cA; const char* nB = has_next ? (const char*)g.Bt + (size_t)nxt.pn * tstep : cB;
;         for (int t = 0; t < nt; t += 2) {
;             const bool last = (t == nt - 2);
;             const char* a1 = cA + (size_t)(t + 1) * kstep;
;             const char* a2 = last ? nA : cA + (size_t)(t + 2) * kstep; const char* b2 = last ? nB : cB + (size_t)(t + 2) * kstep;
;     ...
; #pragma unroll
;         for (int a = 0; a < 2; ++a)
; #pragma unroll
;             for (int b = 0; b < 2; ++b)
; #pragma unroll
;                 for (int m = 0; m < 4; ++m)
; #pragma unroll
;                     for (int n = 0; n < 2; ++n) acc[a][b][m][n] = (f32x4){0.f, 0.f, 0.f, 0.f};
;         cur = nxt; cA = nA; cB = nB; ++ui;
.LBB0_163:
	v_mov_b32_e32 v127, 0
	s_andn2_b64 vcc, exec, s[6:7]
	v_mov_b32_e32 v126, v127
	v_mov_b32_e32 v125, v127
	v_mov_b32_e32 v124, v127
	v_mov_b32_e32 v123, v127
	v_mov_b32_e32 v122, v127
	v_mov_b32_e32 v121, v127
	v_mov_b32_e32 v120, v127
	v_mov_b32_e32 v111, v127
	v_mov_b32_e32 v110, v127
	v_mov_b32_e32 v109, v127
	v_mov_b32_e32 v108, v127
	v_mov_b32_e32 v107, v127
	v_mov_b32_e32 v106, v127
	v_mov_b32_e32 v105, v127
	v_mov_b32_e32 v104, v127
	v_mov_b32_e32 v95, v127
	v_mov_b32_e32 v94, v127
	v_mov_b32_e32 v93, v127
	v_mov_b32_e32 v92, v127
	v_mov_b32_e32 v91, v127
	v_mov_b32_e32 v90, v127
	v_mov_b32_e32 v89, v127
	v_mov_b32_e32 v88, v127
	v_mov_b32_e32 v79, v127
	v_mov_b32_e32 v78, v127
	v_mov_b32_e32 v77, v127
	v_mov_b32_e32 v76, v127
	v_mov_b32_e32 v75, v127
	v_mov_b32_e32 v74, v127
	v_mov_b32_e32 v73, v127
	v_mov_b32_e32 v72, v127
	v_mov_b32_e32 v119, v127
	v_mov_b32_e32 v118, v127
	v_mov_b32_e32 v117, v127
	v_mov_b32_e32 v116, v127
	v_mov_b32_e32 v115, v127
	v_mov_b32_e32 v114, v127
	v_mov_b32_e32 v113, v127
	v_mov_b32_e32 v112, v127
	v_mov_b32_e32 v103, v127
	v_mov_b32_e32 v102, v127
	v_mov_b32_e32 v101, v127
	v_mov_b32_e32 v100, v127
	v_mov_b32_e32 v99, v127
	v_mov_b32_e32 v98, v127
	v_mov_b32_e32 v97, v127
	v_mov_b32_e32 v96, v127
	v_mov_b32_e32 v87, v127
	v_mov_b32_e32 v86, v127
	v_mov_b32_e32 v85, v127
	v_mov_b32_e32 v84, v127
	v_mov_b32_e32 v83, v127
	v_mov_b32_e32 v82, v127
	v_mov_b32_e32 v81, v127
	v_mov_b32_e32 v80, v127
	v_mov_b32_e32 v71, v127
	v_mov_b32_e32 v70, v127
	v_mov_b32_e32 v69, v127
	v_mov_b32_e32 v68, v127
	v_mov_b32_e32 v67, v127
	v_mov_b32_e32 v66, v127
	v_mov_b32_e32 v65, v127
	v_mov_b32_e32 v64, v127
	v_mov_b32_e32 v63, v127
	v_mov_b32_e32 v62, v127
	v_mov_b32_e32 v61, v127
	v_mov_b32_e32 v60, v127
	v_mov_b32_e32 v59, v127
	v_mov_b32_e32 v58, v127
	v_mov_b32_e32 v57, v127
	v_mov_b32_e32 v56, v127
	v_mov_b32_e32 v47, v127
	v_mov_b32_e32 v46, v127
	v_mov_b32_e32 v45, v127
	v_mov_b32_e32 v44, v127
	v_mov_b32_e32 v43, v127
	v_mov_b32_e32 v42, v127
	v_mov_b32_e32 v41, v127
	v_mov_b32_e32 v40, v127
	v_mov_b32_e32 v31, v127
	v_mov_b32_e32 v30, v127
	v_mov_b32_e32 v29, v127
	v_mov_b32_e32 v28, v127
	v_mov_b32_e32 v27, v127
	v_mov_b32_e32 v26, v127
	v_mov_b32_e32 v25, v127
	v_mov_b32_e32 v24, v127
	v_mov_b32_e32 v15, v127
	v_mov_b32_e32 v14, v127
	v_mov_b32_e32 v13, v127
	v_mov_b32_e32 v12, v127
	v_mov_b32_e32 v11, v127
	v_mov_b32_e32 v10, v127
	v_mov_b32_e32 v9, v127
	v_mov_b32_e32 v8, v127
	v_mov_b32_e32 v55, v127
	v_mov_b32_e32 v54, v127
	v_mov_b32_e32 v53, v127
	v_mov_b32_e32 v52, v127
	v_mov_b32_e32 v51, v127
	v_mov_b32_e32 v50, v127
	v_mov_b32_e32 v49, v127
	v_mov_b32_e32 v48, v127
	v_mov_b32_e32 v39, v127
	v_mov_b32_e32 v38, v127
	v_mov_b32_e32 v37, v127
	v_mov_b32_e32 v36, v127
	v_mov_b32_e32 v35, v127
	v_mov_b32_e32 v34, v127
	v_mov_b32_e32 v33, v127
	v_mov_b32_e32 v32, v127
	v_mov_b32_e32 v23, v127
	v_mov_b32_e32 v22, v127
	v_mov_b32_e32 v21, v127
	v_mov_b32_e32 v20, v127
	v_mov_b32_e32 v19, v127
	v_mov_b32_e32 v18, v127
	v_mov_b32_e32 v17, v127
	v_mov_b32_e32 v16, v127
	v_mov_b32_e32 v7, v127
	v_mov_b32_e32 v6, v127
	v_mov_b32_e32 v5, v127
	v_mov_b32_e32 v4, v127
	v_mov_b32_e32 v3, v127
	v_mov_b32_e32 v2, v127
	v_mov_b32_e32 v1, v127
	v_mov_b32_e32 v0, v127
	s_cbranch_vccnz .LBB0_166
	s_add_u32 s42, s18, 0x100
	s_addc_u32 s43, s19, 0
	s_add_u32 s16, s16, 0x80
	v_mov_b32_e32 v0, 0
	s_addc_u32 s17, s17, 0
	s_mov_b32 s18, 0
	v_mov_b32_e32 v1, v0
	v_mov_b32_e32 v2, v0
	v_mov_b32_e32 v3, v0
	v_mov_b32_e32 v4, v0
	v_mov_b32_e32 v5, v0
	v_mov_b32_e32 v6, v0
	v_mov_b32_e32 v7, v0
	v_mov_b32_e32 v16, v0
	v_mov_b32_e32 v17, v0
	v_mov_b32_e32 v18, v0
	v_mov_b32_e32 v19, v0
	v_mov_b32_e32 v20, v0
	v_mov_b32_e32 v21, v0
	v_mov_b32_e32 v22, v0
	v_mov_b32_e32 v23, v0
	v_mov_b32_e32 v32, v0
	v_mov_b32_e32 v33, v0
	v_mov_b32_e32 v34, v0
	v_mov_b32_e32 v35, v0
	v_mov_b32_e32 v36, v0
	v_mov_b32_e32 v37, v0
	v_mov_b32_e32 v38, v0
	v_mov_b32_e32 v39, v0
	v_mov_b32_e32 v48, v0
	v_mov_b32_e32 v49, v0
	v_mov_b32_e32 v50, v0
	v_mov_b32_e32 v51, v0
	v_mov_b32_e32 v52, v0
	v_mov_b32_e32 v53, v0
	v_mov_b32_e32 v54, v0
	v_mov_b32_e32 v55, v0
	v_mov_b32_e32 v8, v0
	v_mov_b32_e32 v9, v0
	v_mov_b32_e32 v10, v0
	v_mov_b32_e32 v11, v0
	v_mov_b32_e32 v12, v0
	v_mov_b32_e32 v13, v0
	v_mov_b32_e32 v14, v0
	v_mov_b32_e32 v15, v0
	v_mov_b32_e32 v24, v0
	v_mov_b32_e32 v25, v0
	v_mov_b32_e32 v26, v0
	v_mov_b32_e32 v27, v0
	v_mov_b32_e32 v28, v0
	v_mov_b32_e32 v29, v0
	v_mov_b32_e32 v30, v0
	v_mov_b32_e32 v31, v0
	v_mov_b32_e32 v40, v0
	v_mov_b32_e32 v41, v0
	v_mov_b32_e32 v42, v0
	v_mov_b32_e32 v43, v0
	v_mov_b32_e32 v44, v0
	v_mov_b32_e32 v45, v0
	v_mov_b32_e32 v46, v0
	v_mov_b32_e32 v47, v0
	v_mov_b32_e32 v56, v0
	v_mov_b32_e32 v57, v0
	v_mov_b32_e32 v58, v0
	v_mov_b32_e32 v59, v0
	v_mov_b32_e32 v60, v0
	v_mov_b32_e32 v61, v0
	v_mov_b32_e32 v62, v0
	v_mov_b32_e32 v63, v0
	v_mov_b32_e32 v64, v0
	v_mov_b32_e32 v65, v0
	v_mov_b32_e32 v66, v0
	v_mov_b32_e32 v67, v0
	v_mov_b32_e32 v68, v0
	v_mov_b32_e32 v69, v0
	v_mov_b32_e32 v70, v0
	v_mov_b32_e32 v71, v0
	v_mov_b32_e32 v80, v0
	v_mov_b32_e32 v81, v0
	v_mov_b32_e32 v82, v0
	v_mov_b32_e32 v83, v0
	v_mov_b32_e32 v84, v0
	v_mov_b32_e32 v85, v0
	v_mov_b32_e32 v86, v0
	v_mov_b32_e32 v87, v0
	v_mov_b32_e32 v96, v0
	v_mov_b32_e32 v97, v0
	v_mov_b32_e32 v98, v0
	v_mov_b32_e32 v99, v0
	v_mov_b32_e32 v100, v0
	v_mov_b32_e32 v101, v0
	v_mov_b32_e32 v102, v0
	v_mov_b32_e32 v103, v0
	v_mov_b32_e32 v112, v0
	v_mov_b32_e32 v113, v0
	v_mov_b32_e32 v114, v0
	v_mov_b32_e32 v115, v0
	v_mov_b32_e32 v116, v0
	v_mov_b32_e32 v117, v0
	v_mov_b32_e32 v118, v0
	v_mov_b32_e32 v119, v0
	v_mov_b32_e32 v72, v0
	v_mov_b32_e32 v73, v0
	v_mov_b32_e32 v74, v0
	v_mov_b32_e32 v75, v0
	v_mov_b32_e32 v76, v0
	v_mov_b32_e32 v77, v0
	v_mov_b32_e32 v78, v0
	v_mov_b32_e32 v79, v0
	v_mov_b32_e32 v88, v0
	v_mov_b32_e32 v89, v0
	v_mov_b32_e32 v90, v0
	v_mov_b32_e32 v91, v0
	v_mov_b32_e32 v92, v0
	v_mov_b32_e32 v93, v0
	v_mov_b32_e32 v94, v0
	v_mov_b32_e32 v95, v0
	v_mov_b32_e32 v104, v0
	v_mov_b32_e32 v105, v0
	v_mov_b32_e32 v106, v0
	v_mov_b32_e32 v107, v0
	v_mov_b32_e32 v108, v0
	v_mov_b32_e32 v109, v0
	v_mov_b32_e32 v110, v0
	v_mov_b32_e32 v111, v0
	v_mov_b32_e32 v120, v0
	v_mov_b32_e32 v121, v0
	v_mov_b32_e32 v122, v0
	v_mov_b32_e32 v123, v0
	v_mov_b32_e32 v124, v0
	v_mov_b32_e32 v125, v0
	v_mov_b32_e32 v126, v0
	v_mov_b32_e32 v127, v0
	s_mov_b64 s[48:49], 0x80
	v_readfirstlane_b32 s90, v192
	s_lshr_b32 s90, s90, 8
	s_cmp_eq_u32 s90, 0
	s_cbranch_scc0 .Lprio_skip_1
	s_setprio 1

; template <class Epi>
; __device__ __forceinline__ void gemm_phase(LAS unsigned char* lds, const Gemm g, const StaticOrder& S, const Epi& E) {
;     ...
;         const bool has_next = S.next(ui + 1, nxt);
;         const char* nA = has_next ? (const char*)g.A + (size_t)nxt.pm * tstep : cA; const char* nB = has_next ? (const char*)g.Bt + (size_t)nxt.pn * tstep : cB;
;         for (int t = 0; t < nt; t += 2) {
;             const bool last = (t == nt - 2);
;             const char* a1 = cA + (size_t)(t + 1) * kstep;
;             const char* a2 = last ? nA : cA + (size_t)(t + 2) * kstep; const char* b2 = last ? nB : cB + (size_t)(t + 2) * kstep;
;     ...
; #pragma unroll
;         for (int a = 0; a < 2; ++a)
; #pragma unroll
;             for (int b = 0; b < 2; ++b)
; #pragma unroll
;                 for (int m = 0; m < 4; ++m)
; #pragma unroll
;                     for (int n = 0; n < 2; ++n) acc[a][b][m][n] = (f32x4){0.f, 0.f, 0.f, 0.f};
;         cur = nxt; cA = nA; cB = nB; ++ui;
.LBB0_526:
	v_mov_b32_e32 v127, 0
	s_andn2_b64 vcc, exec, s[6:7]
	v_mov_b32_e32 v126, v127
	v_mov_b32_e32 v125, v127
	v_mov_b32_e32 v124, v127
	v_mov_b32_e32 v123, v127
	v_mov_b32_e32 v122, v127
	v_mov_b32_e32 v121, v127
	v_mov_b32_e32 v120, v127
	v_mov_b32_e32 v111, v127
	v_mov_b32_e32 v110, v127
	v_mov_b32_e32 v109, v127
	v_mov_b32_e32 v108, v127
	v_mov_b32_e32 v107, v127
	v_mov_b32_e32 v106, v127
	v_mov_b32_e32 v105, v127
	v_mov_b32_e32 v104, v127
	v_mov_b32_e32 v95, v127
	v_mov_b32_e32 v94, v127
	v_mov_b32_e32 v93, v127
	v_mov_b32_e32 v92, v127
	v_mov_b32_e32 v91, v127
	v_mov_b32_e32 v90, v127
	v_mov_b32_e32 v89, v127
	v_mov_b32_e32 v88, v127
	v_mov_b32_e32 v79, v127
	v_mov_b32_e32 v78, v127
	v_mov_b32_e32 v77, v127
	v_mov_b32_e32 v76, v127
	v_mov_b32_e32 v75, v127
	v_mov_b32_e32 v74, v127
	v_mov_b32_e32 v73, v127
	v_mov_b32_e32 v72, v127
	v_mov_b32_e32 v119, v127
	v_mov_b32_e32 v118, v127
	v_mov_b32_e32 v117, v127
	v_mov_b32_e32 v116, v127
	v_mov_b32_e32 v115, v127
	v_mov_b32_e32 v114, v127
	v_mov_b32_e32 v113, v127
	v_mov_b32_e32 v112, v127
	v_mov_b32_e32 v103, v127
	v_mov_b32_e32 v102, v127
	v_mov_b32_e32 v101, v127
	v_mov_b32_e32 v100, v127
	v_mov_b32_e32 v99, v127
	v_mov_b32_e32 v98, v127
	v_mov_b32_e32 v97, v127
	v_mov_b32_e32 v96, v127
	v_mov_b32_e32 v87, v127
	v_mov_b32_e32 v86, v127
	v_mov_b32_e32 v85, v127
	v_mov_b32_e32 v84, v127
	v_mov_b32_e32 v83, v127
	v_mov_b32_e32 v82, v127
	v_mov_b32_e32 v81, v127
	v_mov_b32_e32 v80, v127
	v_mov_b32_e32 v71, v127
	v_mov_b32_e32 v70, v127
	v_mov_b32_e32 v69, v127
	v_mov_b32_e32 v68, v127
	v_mov_b32_e32 v67, v127
	v_mov_b32_e32 v66, v127
	v_mov_b32_e32 v65, v127
	v_mov_b32_e32 v64, v127
	v_mov_b32_e32 v63, v127
	v_mov_b32_e32 v62, v127
	v_mov_b32_e32 v61, v127
	v_mov_b32_e32 v60, v127
	v_mov_b32_e32 v59, v127
	v_mov_b32_e32 v58, v127
	v_mov_b32_e32 v57, v127
	v_mov_b32_e32 v56, v127
	v_mov_b32_e32 v47, v127
	v_mov_b32_e32 v46, v127
	v_mov_b32_e32 v45, v127
	v_mov_b32_e32 v44, v127
	v_mov_b32_e32 v43, v127
	v_mov_b32_e32 v42, v127
	v_mov_b32_e32 v41, v127
	v_mov_b32_e32 v40, v127
	v_mov_b32_e32 v31, v127
	v_mov_b32_e32 v30, v127
	v_mov_b32_e32 v29, v127
	v_mov_b32_e32 v28, v127
	v_mov_b32_e32 v27, v127
	v_mov_b32_e32 v26, v127
	v_mov_b32_e32 v25, v127
	v_mov_b32_e32 v24, v127
	v_mov_b32_e32 v15, v127
	v_mov_b32_e32 v14, v127
	v_mov_b32_e32 v13, v127
	v_mov_b32_e32 v12, v127
	v_mov_b32_e32 v11, v127
	v_mov_b32_e32 v10, v127
	v_mov_b32_e32 v9, v127
	v_mov_b32_e32 v8, v127
	v_mov_b32_e32 v55, v127
	v_mov_b32_e32 v54, v127
	v_mov_b32_e32 v53, v127
	v_mov_b32_e32 v52, v127
	v_mov_b32_e32 v51, v127
	v_mov_b32_e32 v50, v127
	v_mov_b32_e32 v49, v127
	v_mov_b32_e32 v48, v127
	v_mov_b32_e32 v39, v127
	v_mov_b32_e32 v38, v127
	v_mov_b32_e32 v37, v127
	v_mov_b32_e32 v36, v127
	v_mov_b32_e32 v35, v127
	v_mov_b32_e32 v34, v127
	v_mov_b32_e32 v33, v127
	v_mov_b32_e32 v32, v127
	v_mov_b32_e32 v23, v127
	v_mov_b32_e32 v22, v127
	v_mov_b32_e32 v21, v127
	v_mov_b32_e32 v20, v127
	v_mov_b32_e32 v19, v127
	v_mov_b32_e32 v18, v127
	v_mov_b32_e32 v17, v127
	v_mov_b32_e32 v16, v127
	v_mov_b32_e32 v7, v127
	v_mov_b32_e32 v6, v127
	v_mov_b32_e32 v5, v127
	v_mov_b32_e32 v4, v127
	v_mov_b32_e32 v3, v127
	v_mov_b32_e32 v2, v127
	v_mov_b32_e32 v1, v127
	v_mov_b32_e32 v0, v127
	s_cbranch_vccnz .LBB0_529
	s_add_u32 s40, s18, 0x100
	s_addc_u32 s41, s19, 0
	s_add_u32 s16, s16, 0x80
	v_mov_b32_e32 v0, 0
	s_addc_u32 s17, s17, 0
	s_mov_b32 s18, 0
	v_mov_b32_e32 v1, v0
	v_mov_b32_e32 v2, v0
	v_mov_b32_e32 v3, v0
	v_mov_b32_e32 v4, v0
	v_mov_b32_e32 v5, v0
	v_mov_b32_e32 v6, v0
	v_mov_b32_e32 v7, v0
	v_mov_b32_e32 v16, v0
	v_mov_b32_e32 v17, v0
	v_mov_b32_e32 v18, v0
	v_mov_b32_e32 v19, v0
	v_mov_b32_e32 v20, v0
	v_mov_b32_e32 v21, v0
	v_mov_b32_e32 v22, v0
	v_mov_b32_e32 v23, v0
	v_mov_b32_e32 v32, v0
	v_mov_b32_e32 v33, v0
	v_mov_b32_e32 v34, v0
	v_mov_b32_e32 v35, v0
	v_mov_b32_e32 v36, v0
	v_mov_b32_e32 v37, v0
	v_mov_b32_e32 v38, v0
	v_mov_b32_e32 v39, v0
	v_mov_b32_e32 v48, v0
	v_mov_b32_e32 v49, v0
	v_mov_b32_e32 v50, v0
	v_mov_b32_e32 v51, v0
	v_mov_b32_e32 v52, v0
	v_mov_b32_e32 v53, v0
	v_mov_b32_e32 v54, v0
	v_mov_b32_e32 v55, v0
	v_mov_b32_e32 v8, v0
	v_mov_b32_e32 v9, v0
	v_mov_b32_e32 v10, v0
	v_mov_b32_e32 v11, v0
	v_mov_b32_e32 v12, v0
	v_mov_b32_e32 v13, v0
	v_mov_b32_e32 v14, v0
	v_mov_b32_e32 v15, v0
	v_mov_b32_e32 v24, v0
	v_mov_b32_e32 v25, v0
	v_mov_b32_e32 v26, v0
	v_mov_b32_e32 v27, v0
	v_mov_b32_e32 v28, v0
	v_mov_b32_e32 v29, v0
	v_mov_b32_e32 v30, v0
	v_mov_b32_e32 v31, v0
	v_mov_b32_e32 v40, v0
	v_mov_b32_e32 v41, v0
	v_mov_b32_e32 v42, v0
	v_mov_b32_e32 v43, v0
	v_mov_b32_e32 v44, v0
	v_mov_b32_e32 v45, v0
	v_mov_b32_e32 v46, v0
	v_mov_b32_e32 v47, v0
	v_mov_b32_e32 v56, v0
	v_mov_b32_e32 v57, v0
	v_mov_b32_e32 v58, v0
	v_mov_b32_e32 v59, v0
	v_mov_b32_e32 v60, v0
	v_mov_b32_e32 v61, v0
	v_mov_b32_e32 v62, v0
	v_mov_b32_e32 v63, v0
	v_mov_b32_e32 v64, v0
	v_mov_b32_e32 v65, v0
	v_mov_b32_e32 v66, v0
	v_mov_b32_e32 v67, v0
	v_mov_b32_e32 v68, v0
	v_mov_b32_e32 v69, v0
	v_mov_b32_e32 v70, v0
	v_mov_b32_e32 v71, v0
	v_mov_b32_e32 v80, v0
	v_mov_b32_e32 v81, v0
	v_mov_b32_e32 v82, v0
	v_mov_b32_e32 v83, v0
	v_mov_b32_e32 v84, v0
	v_mov_b32_e32 v85, v0
	v_mov_b32_e32 v86, v0
	v_mov_b32_e32 v87, v0
	v_mov_b32_e32 v96, v0
	v_mov_b32_e32 v97, v0
	v_mov_b32_e32 v98, v0
	v_mov_b32_e32 v99, v0
	v_mov_b32_e32 v100, v0
	v_mov_b32_e32 v101, v0
	v_mov_b32_e32 v102, v0
	v_mov_b32_e32 v103, v0
	v_mov_b32_e32 v112, v0
	v_mov_b32_e32 v113, v0
	v_mov_b32_e32 v114, v0
	v_mov_b32_e32 v115, v0
	v_mov_b32_e32 v116, v0
	v_mov_b32_e32 v117, v0
	v_mov_b32_e32 v118, v0
	v_mov_b32_e32 v119, v0
	v_mov_b32_e32 v72, v0
	v_mov_b32_e32 v73, v0
	v_mov_b32_e32 v74, v0
	v_mov_b32_e32 v75, v0
	v_mov_b32_e32 v76, v0
	v_mov_b32_e32 v77, v0
	v_mov_b32_e32 v78, v0
	v_mov_b32_e32 v79, v0
	v_mov_b32_e32 v88, v0
	v_mov_b32_e32 v89, v0
	v_mov_b32_e32 v90, v0
	v_mov_b32_e32 v91, v0
	v_mov_b32_e32 v92, v0
	v_mov_b32_e32 v93, v0
	v_mov_b32_e32 v94, v0
	v_mov_b32_e32 v95, v0
	v_mov_b32_e32 v104, v0
	v_mov_b32_e32 v105, v0
	v_mov_b32_e32 v106, v0
	v_mov_b32_e32 v107, v0
	v_mov_b32_e32 v108, v0
	v_mov_b32_e32 v109, v0
	v_mov_b32_e32 v110, v0
	v_mov_b32_e32 v111, v0
	v_mov_b32_e32 v120, v0
	v_mov_b32_e32 v121, v0
	v_mov_b32_e32 v122, v0
	v_mov_b32_e32 v123, v0
	v_mov_b32_e32 v124, v0
	v_mov_b32_e32 v125, v0
	v_mov_b32_e32 v126, v0
	v_mov_b32_e32 v127, v0
	s_mov_b64 s[46:47], 0x80
	v_readfirstlane_b32 s90, v192
	s_lshr_b32 s90, s90, 8
	s_cmp_eq_u32 s90, 0
	s_cbranch_scc0 .Lprio_skip_3
	s_setprio 1
